# combine preheader: the hoisted out_norm_g loads issued together with the first-row loads (one serial round trip less per combine phase)
# speedup vs baseline: 1.0115x; 1.0017x over previous
; __device__ __forceinline__ f32x4 cvt4(const f16x8 v, int hi) { return (f32x4){(float)v[4 * hi], (float)v[4 * hi + 1], (float)v[4 * hi + 2], (float)v[4 * hi + 3]}; }
; __device__ __forceinline__ float wave_sum(float v) { v = row_sum16(v); return (rlanef(v, 0) + rlanef(v, 16)) + (rlanef(v, 32) + rlanef(v, 48)); }
; __device__ __forceinline__ void phase_combine(const Params& P, int l, bool write_lo) {
;     ...
;     const int G8 = (gridDim.x % 8 == 0 && (MTOK / 8) % (int)gridDim.x == 0) ? 1 : 0;
;     const int r0x = G8 ? (MTOK / 8) * ((int)blockIdx.x & 7) + ((int)blockIdx.x >> 3) * 8 + (tid >> 6) : gw, rsx = G8 ? NGW / 8 : NGW, rex = G8 ? (MTOK / 8) * (((int)blockIdx.x & 7) + 1) : MTOK;
;     if (r0x < rex) CMB_LOAD(r0x);
;     for (int row = r0x; row < rex; row += rsx) {
;         const f16x8 raw = nraw; f32x2 o0[4], o1[4]; float L0[4], L1[4];
; #pragma unroll
;         for (int h = 0; h < 4; ++h) { o0[h] = no0[h]; o1[h] = no1[h]; L0[h] = nL0[h]; L1[h] = nL1[h]; }
;         if (row + rsx < rex) CMB_LOAD(row + rsx);
;         { const int g = 1;
;             const f32x4 v0 = cvt4(raw, 0), v1 = cvt4(raw, 1);
;             float ss = v0[0] * v0[0] + v0[1] * v0[1] + v0[2] * v0[2] + v0[3] * v0[3] + v1[0] * v1[0] + v1[1] * v1[1] + v1[2] * v1[2] + v1[3] * v1[3];
;             ss = wave_sum(ss);
;             const float rstd = 1.0f / sqrtf(ss * (1.0f / GW) + EPS);
;             const f32x4 g0 = *(const f32x4*)(og + GW * g + 8 * lane), g1 = *(const f32x4*)(og + GW * g + 8 * lane + 4);
;             *(f16x8*)(yh + (size_t)row * DM + GW * g + 8 * lane) = pack8(((v0 * rstd) * g0) * SA, ((v1 * rstd) * g1) * SA); }
;         f32x2 yc[4]; float ss = 0.f;
; #pragma unroll
;         for (int h = 0; h < 4; ++h) { yc[h] = (o0[h] + o1[h]) / (L0[h] + L1[h]); ss += yc[h][0] * yc[h][0] + yc[h][1] * yc[h][1]; }
;         ss = wave_sum(ss);
;         const float rstd = 1.0f / sqrtf(ss * (1.0f / GW) + EPS);
; #pragma unroll
;         for (int h = 0; h < 4; ++h) { const int c = 2 * GW + 128 * h + 2 * lane; const f32x2 gg = *(const f32x2*)(og + c);
.LBB0_1040:
	s_or_b64 exec, exec, s[12:13]
	s_and_b64 s[8:9], s[8:9], exec
	v_readlane_b32 s3, v252, 54
	v_readlane_b32 s4, v247, 31
	s_cselect_b32 s8, s3, s97
	s_lshl_b32 s56, s4, 11
	s_lshl_b64 s[12:13], s[56:57], 2
	v_readlane_b32 s60, v251, 0
	v_lshlrev_b32_e32 v5, 1, v21
	v_readlane_b32 s61, v251, 1
	s_add_u32 s12, s60, s12
	s_addc_u32 s13, s61, s13
	v_lshlrev_b32_e32 v2, 2, v2
	v_lshlrev_b32_e32 v5, 2, v5
	v_lshl_add_u64 v[40:41], s[12:13], 0, v[2:3]
	v_or_b32_e32 v2, 0x1000, v5
	v_lshl_add_u64 v[42:43], s[12:13], 0, v[2:3]
	v_or_b32_e32 v2, 0x1200, v5
	v_lshl_add_u64 v[44:45], s[12:13], 0, v[2:3]
	v_or_b32_e32 v2, 0x1400, v5
	v_lshl_add_u64 v[46:47], s[12:13], 0, v[2:3]
	v_or_b32_e32 v2, 0x1600, v5
	v_lshl_add_u64 v[48:49], s[12:13], 0, v[2:3]
	v_lshlrev_b32_e32 v2, 2, v21
	v_mov_b32_e32 v5, v3
	v_lshl_add_u64 v[50:51], v[6:7], 0, v[2:3]
	v_lshl_add_u64 v[6:7], v[6:7], 0, v[4:5]
	s_mov_b64 s[20:21], 0x13ff1400
	s_add_i32 s2, s8, s2
	v_lshl_add_u64 v[52:53], v[6:7], 0, s[20:21]
	v_add_u32_e32 v6, s2, v20
	v_ashrrev_i32_e32 v7, 31, v6
	v_readlane_b32 s5, v247, 32
	v_lshlrev_b32_e32 v37, 2, v6
	v_lshlrev_b64 v[6:7], 12, v[6:7]
	v_or_b32_e32 v6, v6, v4
	s_mov_b64 s[4:5], 0x2dff1400
	s_ashr_i32 s9, s8, 31
	v_lshl_add_u64 v[54:55], v[6:7], 0, s[4:5]
	global_load_dwordx4 v[100:103], v[40:41], off offset:2064
	global_load_dwordx4 v[104:107], v[40:41], off offset:2048
	global_load_dwordx2 v[108:109], v[42:43], off
	global_load_dwordx2 v[110:111], v[44:45], off
	global_load_dwordx2 v[112:113], v[46:47], off
	global_load_dwordx2 v[114:115], v[48:49], off
	s_waitcnt vmcnt(14)
	v_mov_b64_e32 v[20:21], v[32:33]
	s_waitcnt vmcnt(7)
	v_mov_b64_e32 v[4:5], v[12:13]
	s_waitcnt vmcnt(6)
	v_mov_b64_e32 v[24:25], v[28:29]
	s_waitcnt vmcnt(0)
	s_lshl_b64 s[12:13], s[8:9], 12
	s_lshl_b32 s3, s8, 2
	s_mov_b64 s[20:21], 0
	s_mov_b64 s[26:27], s[90:91]
	v_mov_b64_e32 v[22:23], v[34:35]
	v_mov_b64_e32 v[6:7], v[14:15]
	v_mov_b64_e32 v[8:9], v[16:17]
	v_mov_b64_e32 v[10:11], v[18:19]
	v_mov_b64_e32 v[26:27], v[30:31]
	v_mov_b64_e32 v[62:63], v[64:65]
	v_mov_b64_e32 v[60:61], v[66:67]
	v_mov_b64_e32 v[58:59], v[68:69]
	v_mov_b64_e32 v[56:57], v[70:71]
	v_mov_b32_e32 v83, v84
	v_mov_b32_e32 v82, v85
	v_mov_b32_e32 v81, v86
	v_mov_b32_e32 v80, v87
	v_readlane_b32 s62, v251, 2
	v_readlane_b32 s63, v251, 3
	v_readlane_b32 s64, v251, 4
	v_readlane_b32 s65, v251, 5
	v_readlane_b32 s66, v251, 6
	v_readlane_b32 s67, v251, 7
	s_branch .LBB0_1043
